# attention: 4-slot K/V LDS rings, each half-step publishes the tiles it loaded itself, workgroup barrier only every second 64-key tile (loop unrolled to 4 half-steps)
# speedup vs baseline: 1.0141x; 1.0141x over previous
.LBB0_883:
	ds_read_b128 v[60:63], v201
	ds_read_b128 v[64:67], v201 offset:1024
	ds_read_b128 v[76:79], v201 offset:3072
	ds_read_b128 v[80:83], v201 offset:2048
	ds_read_b128 v[88:91], v201 offset:6144
	ds_read_b128 v[152:155], v201 offset:7168
	ds_read_b128 v[184:187], v201 offset:9216
	ds_read_b128 v[188:191], v201 offset:8192
	s_waitcnt lgkmcnt(7)
	v_mfma_f32_16x16x32_bf16 v[68:71], v[60:63], v[12:15], v[44:47]
	v_mfma_f32_16x16x32_bf16 v[60:63], v[60:63], v[16:19], v[48:51]
	s_waitcnt lgkmcnt(5)
	v_mfma_f32_16x16x32_bf16 v[84:87], v[76:79], v[12:15], v[44:47]
	v_mfma_f32_16x16x32_bf16 v[76:79], v[76:79], v[16:19], v[48:51]
	v_mfma_f32_16x16x32_bf16 v[68:71], v[64:67], v[4:7], v[68:71]
	v_mfma_f32_16x16x32_bf16 v[60:63], v[64:67], v[20:23], v[60:63]
	ds_read_b128 v[64:67], v201 offset:4096
	ds_read_b128 v[204:207], v201 offset:5120
	s_waitcnt lgkmcnt(5)
	v_mfma_f32_16x16x32_bf16 v[180:183], v[88:91], v[12:15], v[44:47]
	v_mfma_f32_16x16x32_bf16 v[88:91], v[88:91], v[16:19], v[48:51]
	s_waitcnt lgkmcnt(3)
	v_mfma_f32_16x16x32_bf16 v[192:195], v[184:187], v[12:15], v[44:47]
	s_waitcnt lgkmcnt(1)
	v_mfma_f32_16x16x32_bf16 v[208:211], v[64:67], v[4:7], v[84:87]
	v_mfma_f32_16x16x32_bf16 v[64:67], v[64:67], v[20:23], v[76:79]
	s_nop 2
	ds_read_b128 v[76:79], v201 offset:10240
	ds_read_b128 v[216:219], v201 offset:11264
	v_mfma_f32_16x16x32_bf16 v[184:187], v[184:187], v[16:19], v[48:51]
	v_mfma_f32_16x16x32_bf16 v[180:183], v[152:155], v[4:7], v[180:183]
	v_mfma_f32_16x16x32_bf16 v[212:215], v[152:155], v[20:23], v[88:91]
	v_exp_f32_e32 v153, v72
	v_exp_f32_e32 v152, v116
	v_exp_f32_e32 v155, v73
	s_waitcnt lgkmcnt(1)
	v_mfma_f32_16x16x32_bf16 v[192:195], v[76:79], v[4:7], v[192:195]
	v_exp_f32_e32 v154, v117
	s_nop 0
	v_cvt_pk_bf16_f32 v116, v152, v154
	v_mfma_f32_16x16x32_bf16 v[220:223], v[76:79], v[20:23], v[184:187]
	v_mfma_f32_16x16x32_bf16 v[84:87], v[80:83], v[8:11], v[68:71]
	s_nop 1
	v_exp_f32_e32 v187, v111
	v_exp_f32_e32 v185, v75
	v_exp_f32_e32 v184, v119
	v_mfma_f32_16x16x32_bf16 v[88:91], v[80:83], v[24:27], v[60:63]
	v_exp_f32_e32 v186, v115
	v_mfma_f32_16x16x32_bf16 v[80:83], v[204:207], v[24:27], v[64:67]
	v_mfma_f32_16x16x32_bf16 v[60:63], v[188:191], v[8:11], v[180:183]
	v_mfma_f32_16x16x32_bf16 v[68:71], v[188:191], v[24:27], v[212:215]
	v_exp_f32_e32 v191, v109
	v_exp_f32_e32 v189, v110
	v_exp_f32_e32 v181, v74
	s_waitcnt lgkmcnt(0)
	v_mfma_f32_16x16x32_bf16 v[64:67], v[216:219], v[8:11], v[192:195]
	v_exp_f32_e32 v180, v118
	v_exp_f32_e32 v190, v113
	v_exp_f32_e32 v188, v114
	v_exp_f32_e32 v193, v108
	ds_read_b128 v[108:111], v200 offset:32768
	v_exp_f32_e32 v192, v112
	v_mfma_f32_16x16x32_bf16 v[76:79], v[204:207], v[8:11], v[208:211]
	ds_read_b128 v[204:207], v200 offset:34816
	s_nop 1
	ds_read_b128 v[208:211], v200 offset:33792
	v_cvt_pk_bf16_f32 v112, v153, v155
	v_cvt_pk_bf16_f32 v113, v181, v185
	v_cvt_pk_bf16_f32 v114, v193, v191
	v_cvt_pk_bf16_f32 v115, v189, v187
	v_cvt_pk_bf16_f32 v117, v180, v184
	v_cvt_pk_bf16_f32 v118, v192, v190
	v_cvt_pk_bf16_f32 v119, v188, v186
	v_mfma_f32_16x16x32_bf16 v[72:75], v[216:219], v[24:27], v[220:223]
	v_exp_f32_e32 v183, v100
	v_exp_f32_e32 v182, v104
	v_exp_f32_e32 v195, v101
	s_waitcnt lgkmcnt(2)
	v_mfma_f32_16x16x32_bf16 v[148:151], v[108:111], v[112:115], v[148:151]
	v_exp_f32_e32 v194, v105
	v_cvt_pk_bf16_f32 v228, v183, v195
	v_mfma_f32_16x16x32_bf16 v[108:111], v[108:111], v[116:119], v[144:147]
	s_nop 2
	ds_read_b128 v[144:147], v200 offset:36864
	ds_read_b128 v[212:215], v200 offset:35840
	v_cvt_pk_bf16_f32 v232, v182, v194
	s_waitcnt lgkmcnt(3)
	v_mfma_f32_16x16x32_bf16 v[216:219], v[204:207], v[112:115], v[140:143]
	s_nop 2
	v_exp_f32_e32 v141, v102
	v_exp_f32_e32 v140, v106
	v_exp_f32_e32 v143, v103
	v_mfma_f32_16x16x32_bf16 v[100:103], v[204:207], v[116:119], v[136:139]
	v_exp_f32_e32 v142, v107
	ds_read_b128 v[104:107], v200 offset:38912
	s_nop 0
	ds_read_b128 v[136:139], v200 offset:37888
	ds_read_b128 v[220:223], v200 offset:39936
	s_waitcnt lgkmcnt(4)
; #define LAS __attribute__((address_space(3)))
; #define MFMA16(a_, b_, c_) __builtin_amdgcn_mfma_f32_16x16x32_bf16((a_), (b_), (c_), 0, 0, 0)
; DI void attn_phase(LAS unsigned char* lds, const int wid, const bf16_t* Q, const bf16_t* Kn, const bf16_t* Kr, const bf16_t* Vt, bf16_t* O, int G, int c) {
;     ...
;         u32x4 rkn = *(const u32x4*)gkn, rvt = *(const u32x4*)gvt, rkr = {0u, 0u, 0u, 0u};
;         if (tid < 256) rkr = *(const u32x4*)gkr;
;         *(LAS u32x4*)(lds + lkn) = rkn; *(LAS u32x2*)(lds + lvt) = (u32x2){rvt.x, rvt.y}; *(LAS u32x2*)(lds + lvt + 16) = (u32x2){rvt.z, rvt.w}; if (tid < 256) *(LAS u32x4*)(lds + lkr) = rkr;
;         rkn = *(const u32x4*)(gkn + 64 * 512); if (tid < 256) rkr = *(const u32x4*)(gkr + 64 * 32);
;         *(LAS u32x4*)(lds + KS_BYTES + lkn) = rkn; if (tid < 256) *(LAS u32x4*)(lds + KS_BYTES + lkr) = rkr;
;         __syncthreads();
;         { const LAS unsigned char* kp = lds + r16 * KS_STRIDE + qd * 16;
; #pragma unroll
;           for (int t4 = 0; t4 < 4; ++t4) { sa[t4][0] = negm0; sa[t4][1] = negm1; }
; #pragma unroll
;           for (int ks = 0; ks < 3; ++ks)
; #pragma unroll
;             for (int t4 = 0; t4 < 4; ++t4) { const bf16x8 kf = *(const LAS bf16x8*)(kp + t4 * 16 * KS_STRIDE + ks * 64);
;                 sa[t4][0] = MFMA16(kf, qf[0][ks], sa[t4][0]); sa[t4][1] = MFMA16(kf, qf[1][ks], sa[t4][1]); } }
;         __syncthreads();
;         u32x4 akn = *(const u32x4*)(gkn + (size_t)2 * 64 * 512), avt = *(const u32x4*)(gvt + 64), akr = {0u, 0u, 0u, 0u}, bkn, bkr = {0u, 0u, 0u, 0u}, bvt;
;         if (tid < 256) akr = *(const u32x4*)(gkr + (size_t)2 * 64 * 32);
;         if (wid >= 4) __builtin_amdgcn_s_setprio(1);
;         for (int kt = 0; kt < NKT; kt += 2) {
	v_mfma_f32_16x16x32_bf16 v[204:207], v[144:147], v[112:115], v[132:135]
	v_cvt_pk_bf16_f32 v229, v141, v143
	v_cvt_pk_bf16_f32 v233, v140, v142
	s_waitcnt vmcnt(3)
	ds_write_b128 v197, v[32:35] offset:12288
	v_exp_f32_e32 v133, v92
	v_exp_f32_e32 v132, v96
	v_exp_f32_e32 v135, v93
	v_mfma_f32_16x16x32_bf16 v[144:147], v[144:147], v[116:119], v[128:131]
	v_exp_f32_e32 v134, v97
	v_cvt_pk_bf16_f32 v230, v133, v135
	s_nop 0
	v_exp_f32_e32 v129, v94
	s_waitcnt lgkmcnt(3)
	v_mfma_f32_16x16x32_bf16 v[224:227], v[104:107], v[112:115], v[124:127]
	v_exp_f32_e32 v128, v98
	v_cvt_pk_bf16_f32 v234, v132, v134
	s_nop 0
	v_exp_f32_e32 v125, v95
	v_exp_f32_e32 v124, v99
	v_mfma_f32_16x16x32_bf16 v[92:95], v[104:107], v[116:119], v[120:123]
	v_cvt_pk_bf16_f32 v231, v129, v125
	v_cvt_pk_bf16_f32 v235, v128, v124
	s_nop 0
	v_mfma_f32_16x16x32_bf16 v[120:123], v[208:211], v[228:231], v[148:151]
	v_mfma_f32_16x16x32_bf16 v[104:107], v[208:211], v[232:235], v[108:111]
	v_mfma_f32_16x16x32_bf16 v[116:119], v[212:215], v[228:231], v[216:219]
	v_mfma_f32_16x16x32_bf16 v[100:103], v[212:215], v[232:235], v[100:103]
	s_waitcnt lgkmcnt(2)
	v_mfma_f32_16x16x32_bf16 v[112:115], v[136:139], v[228:231], v[204:207]
	v_mfma_f32_16x16x32_bf16 v[96:99], v[136:139], v[232:235], v[144:147]
	s_waitcnt lgkmcnt(1)
	v_mfma_f32_16x16x32_bf16 v[108:111], v[220:223], v[228:231], v[224:227]
	v_mfma_f32_16x16x32_bf16 v[92:95], v[220:223], v[232:235], v[92:95]
	s_and_saveexec_b64 s[48:49], s[10:11]
	ds_write_b128 v199, v[36:39] offset:12288
	s_or_b64 exec, exec, s[48:49]
	v_pk_add_f32 v[126:127], v[152:153], 0 op_sel_hi:[1,0]
	v_pk_add_f32 v[130:131], v[154:155], 0 op_sel_hi:[1,0]
	v_pk_add_f32 v[136:137], v[180:181], 0 op_sel_hi:[1,0]
	v_pk_add_f32 v[138:139], v[184:185], 0 op_sel_hi:[1,0]
	v_pk_add_f32 v[126:127], v[192:193], v[126:127]
	v_pk_add_f32 v[130:131], v[190:191], v[130:131]
	v_pk_add_f32 v[136:137], v[188:189], v[136:137]
	v_pk_add_f32 v[138:139], v[186:187], v[138:139]
	v_pk_add_f32 v[126:127], v[182:183], v[126:127]
	v_pk_add_f32 v[130:131], v[194:195], v[130:131]
	v_pk_add_f32 v[136:137], v[140:141], v[136:137]
	v_pk_add_f32 v[138:139], v[142:143], v[138:139]
	v_pk_add_f32 v[126:127], v[132:133], v[126:127]
	v_pk_add_f32 v[130:131], v[134:135], v[130:131]
	v_pk_add_f32 v[128:129], v[128:129], v[136:137]
	v_pk_add_f32 v[124:125], v[124:125], v[138:139]
	v_pk_add_f32 v[126:127], v[126:127], v[130:131]
	v_pk_add_f32 v[124:125], v[128:129], v[124:125]
	s_and_b32 s26, s9, 7
	v_pk_add_f32 v[124:125], v[126:127], v[124:125]
	s_waitcnt vmcnt(2)
	ds_write2_b64 v177, v[40:41], v[42:43] offset1:32
	v_pk_add_f32 v[184:185], v[2:3], v[124:125]
	v_lshl_add_u32 v2, s26, 6, v160
	s_lshl_b32 s26, s26, 7
	v_ashrrev_i32_e32 v3, 31, v2
	s_add_u32 s16, s28, s16
	v_lshlrev_b64 v[2:3], 17, v[2:3]
	s_addc_u32 s17, s29, s17
	v_lshl_add_u64 v[2:3], s[16:17], 0, v[2:3]
	s_lshl_b64 s[16:17], s[14:15], 19
	s_lshl_b64 s[14:15], s[14:15], 23
	s_or_b32 s14, s14, s26
	v_lshl_add_u64 v[180:181], v[170:171], 0, s[16:17]
	v_lshl_add_u64 v[182:183], v[172:173], 0, s[14:15]
	v_max3_f32 v246, v88, v89, v90
	v_max3_f32 v247, v84, v85, v86
	v_max3_f32 v246, v246, v91, v80
	v_max3_f32 v247, v247, v87, v76
	v_max3_f32 v246, v246, v81, v82
	v_max3_f32 v247, v247, v77, v78
	v_max3_f32 v246, v246, v83, v68
	v_max3_f32 v247, v247, v79, v60
	v_max3_f32 v246, v246, v69, v70
	v_max3_f32 v247, v247, v61, v62
	v_max3_f32 v246, v246, v71, v72
	v_max3_f32 v247, v247, v63, v64
	v_max3_f32 v246, v246, v73, v74
	v_max3_f32 v247, v247, v65, v66
	s_mov_b32 s26, 2
	v_add_u32_e32 v252, 0x10000, v198
	v_add_u32_e32 v253, 0x12000, v198
	v_add_u32_e32 v203, 0xc000, v200
	s_waitcnt vmcnt(0)
	ds_write_b128 v197, v[52:55] offset:40960
	s_and_saveexec_b64 s[14:15], s[10:11]
	ds_write_b128 v199, v[28:31] offset:40960
	s_or_b64 exec, exec, s[14:15]
	ds_write2_b64 v252, v[56:57], v[58:59] offset1:32
	s_waitcnt lgkmcnt(0)
	s_barrier
	s_branch .LBB0_887

.LBB0_895:
	ds_read_b128 v[124:127], v201 offset:12288
	ds_read_b128 v[128:131], v201 offset:13312
	ds_read_b128 v[136:139], v201 offset:15360
	ds_read_b128 v[140:143], v201 offset:14336
	ds_read_b128 v[148:151], v201 offset:18432
	ds_read_b128 v[152:155], v201 offset:19456
	ds_read_b128 v[204:207], v201 offset:21504
	ds_read_b128 v[208:211], v201 offset:20480
	s_waitcnt lgkmcnt(7)
	v_mfma_f32_16x16x32_bf16 v[132:135], v[124:127], v[12:15], v[44:47]
	v_exp_f32_e32 v195, v84
	v_exp_f32_e32 v194, v88
	v_mfma_f32_16x16x32_bf16 v[124:127], v[124:127], v[16:19], v[48:51]
	v_exp_f32_e32 v88, v91
	v_exp_f32_e32 v84, v81
	s_waitcnt lgkmcnt(3)
	v_mfma_f32_16x16x32_bf16 v[190:193], v[148:151], v[12:15], v[44:47]
	v_exp_f32_e32 v81, v78
	v_exp_f32_e32 v79, v79
	v_mfma_f32_16x16x32_bf16 v[148:151], v[148:151], v[16:19], v[48:51]
	v_exp_f32_e32 v78, v83
	v_exp_f32_e32 v61, v61
	v_mfma_f32_16x16x32_bf16 v[144:147], v[136:139], v[12:15], v[44:47]
	v_exp_f32_e32 v63, v63
	v_exp_f32_e32 v83, v64
	v_mfma_f32_16x16x32_bf16 v[136:139], v[136:139], v[16:19], v[48:51]
	v_exp_f32_e32 v64, v74
	v_exp_f32_e32 v67, v67
	s_waitcnt lgkmcnt(1)
	v_mfma_f32_16x16x32_bf16 v[212:215], v[204:207], v[12:15], v[44:47]
	v_exp_f32_e32 v250, v90
	v_mfma_f32_16x16x32_bf16 v[204:207], v[204:207], v[16:19], v[48:51]
	v_mfma_f32_16x16x32_bf16 v[132:135], v[128:131], v[4:7], v[132:135]
	v_mfma_f32_16x16x32_bf16 v[124:127], v[128:131], v[20:23], v[124:127]
	ds_read_b128 v[128:131], v201 offset:16384
	ds_read_b128 v[216:219], v201 offset:17408
	v_mfma_f32_16x16x32_bf16 v[220:223], v[152:155], v[20:23], v[148:151]
	v_exp_f32_e32 v249, v85
	v_exp_f32_e32 v248, v89
	v_exp_f32_e32 v251, v86
	ds_read_b128 v[148:151], v201 offset:22528
	ds_read_b128 v[224:227], v201 offset:23552
	s_waitcnt lgkmcnt(3)
	v_mfma_f32_16x16x32_bf16 v[144:147], v[128:131], v[4:7], v[144:147]
	v_exp_f32_e32 v89, v87
	v_exp_f32_e32 v87, v76
	v_mfma_f32_16x16x32_bf16 v[128:131], v[128:131], v[20:23], v[136:139]
	v_exp_f32_e32 v86, v80
	s_waitcnt lgkmcnt(1)
	v_mfma_f32_16x16x32_bf16 v[204:207], v[148:151], v[20:23], v[204:207]
	v_exp_f32_e32 v85, v77
	v_exp_f32_e32 v80, v82
	v_mfma_f32_16x16x32_bf16 v[136:139], v[152:155], v[4:7], v[190:193]
	v_exp_f32_e32 v77, v60
	v_mfma_f32_16x16x32_bf16 v[212:215], v[148:151], v[4:7], v[212:215]
	v_exp_f32_e32 v76, v68
	v_exp_f32_e32 v60, v69
	v_mfma_f32_16x16x32_bf16 v[148:151], v[140:143], v[8:11], v[132:135]
	v_exp_f32_e32 v69, v62
	v_mfma_f32_16x16x32_bf16 v[152:155], v[140:143], v[24:27], v[124:127]
	v_exp_f32_e32 v68, v70
	v_exp_f32_e32 v62, v71
	v_mfma_f32_16x16x32_bf16 v[140:143], v[216:219], v[8:11], v[144:147]
	v_exp_f32_e32 v82, v72
	v_mfma_f32_16x16x32_bf16 v[144:147], v[216:219], v[24:27], v[128:131]
	v_exp_f32_e32 v71, v65
	v_exp_f32_e32 v70, v73
	s_waitcnt lgkmcnt(0)
	v_mfma_f32_16x16x32_bf16 v[128:131], v[224:227], v[24:27], v[204:207]
	v_exp_f32_e32 v65, v66
	ds_read_b128 v[204:207], v200 offset:24576
	v_mfma_f32_16x16x32_bf16 v[132:135], v[208:211], v[8:11], v[136:139]
	v_exp_f32_e32 v66, v75
	v_cvt_pk_bf16_f32 v90, v77, v61
	v_mfma_f32_16x16x32_bf16 v[136:139], v[208:211], v[24:27], v[220:223]
	v_cvt_pk_bf16_f32 v208, v195, v249
	v_cvt_pk_bf16_f32 v209, v251, v89
	v_cvt_pk_bf16_f32 v210, v87, v85
	v_mfma_f32_16x16x32_bf16 v[124:127], v[224:227], v[8:11], v[212:215]
	v_cvt_pk_bf16_f32 v211, v81, v79
	ds_read_b128 v[216:219], v200 offset:26624
	ds_read_b128 v[220:223], v200 offset:25600
	v_cvt_pk_bf16_f32 v212, v194, v248
	v_cvt_pk_bf16_f32 v213, v250, v88
	v_cvt_pk_bf16_f32 v214, v86, v84
	v_cvt_pk_bf16_f32 v215, v80, v78
	s_waitcnt lgkmcnt(2)
	v_mfma_f32_16x16x32_bf16 v[120:123], v[204:207], v[208:211], v[120:123]
	v_cvt_pk_bf16_f32 v91, v69, v63
	v_mfma_f32_16x16x32_bf16 v[104:107], v[204:207], v[212:215], v[104:107]
	ds_read_b128 v[204:207], v200 offset:28672
	ds_read_b128 v[224:227], v200 offset:27648
	s_waitcnt lgkmcnt(3)
	v_mfma_f32_16x16x32_bf16 v[228:231], v[216:219], v[208:211], v[116:119]
	v_mfma_f32_16x16x32_bf16 v[100:103], v[216:219], v[212:215], v[100:103]
	s_nop 1
	ds_read_b128 v[116:119], v200 offset:30720
	ds_read_b128 v[216:219], v200 offset:29696
	s_waitcnt lgkmcnt(3)
	v_mfma_f32_16x16x32_bf16 v[232:235], v[204:207], v[208:211], v[112:115]
	v_mfma_f32_16x16x32_bf16 v[96:99], v[204:207], v[212:215], v[96:99]
	ds_read_b128 v[204:207], v200 offset:31744
	s_waitcnt lgkmcnt(2)
	v_mfma_f32_16x16x32_bf16 v[208:211], v[116:119], v[208:211], v[108:111]
	v_mfma_f32_16x16x32_bf16 v[72:75], v[116:119], v[212:215], v[92:95]
	v_cvt_pk_bf16_f32 v212, v76, v60
	v_cvt_pk_bf16_f32 v213, v68, v62
	v_cvt_pk_bf16_f32 v214, v82, v70
	v_cvt_pk_bf16_f32 v92, v83, v71
	v_cvt_pk_bf16_f32 v93, v65, v67
	v_cvt_pk_bf16_f32 v215, v64, v66
	s_nop 0
	v_mfma_f32_16x16x32_bf16 v[120:123], v[220:223], v[90:93], v[120:123]
	v_mfma_f32_16x16x32_bf16 v[116:119], v[220:223], v[212:215], v[104:107]
	v_max3_f32 v244, v152, v153, v154
	v_max3_f32 v245, v148, v149, v150
	v_mfma_f32_16x16x32_bf16 v[112:115], v[224:227], v[90:93], v[228:231]
	v_max3_f32 v244, v244, v155, v144
	v_max3_f32 v245, v245, v151, v140
	v_mfma_f32_16x16x32_bf16 v[108:111], v[224:227], v[212:215], v[100:103]
	v_max3_f32 v244, v244, v145, v146
	v_max3_f32 v245, v245, v141, v142
	s_waitcnt lgkmcnt(1)
	v_mfma_f32_16x16x32_bf16 v[104:107], v[216:219], v[90:93], v[232:235]
	v_max3_f32 v244, v244, v147, v136
	v_max3_f32 v245, v245, v143, v132
	v_mfma_f32_16x16x32_bf16 v[100:103], v[216:219], v[212:215], v[96:99]
	v_max3_f32 v244, v244, v137, v138
	v_max3_f32 v245, v245, v133, v134
	s_waitcnt lgkmcnt(0)
	v_mfma_f32_16x16x32_bf16 v[92:95], v[204:207], v[90:93], v[208:211]
	v_max3_f32 v244, v244, v139, v128
	v_max3_f32 v245, v245, v135, v124
	v_mfma_f32_16x16x32_bf16 v[96:99], v[204:207], v[212:215], v[72:75]
	v_max3_f32 v244, v244, v129, v130
	v_max3_f32 v245, v245, v125, v126
	s_waitcnt vmcnt(0)
	ds_write_b128 v197, v[32:35] offset:53248
	s_and_saveexec_b64 s[16:17], s[10:11]
	ds_write_b128 v199, v[36:39] offset:53248
	s_or_b64 exec, exec, s[16:17]
.LBB0_899:
	ds_write2_b64 v253, v[40:41], v[42:43] offset1:32
	v_lshl_add_u64 v[52:53], v[186:187], 0, s[58:59]
	global_load_dwordx4 v[52:55], v[52:53], off
	s_and_saveexec_b64 s[16:17], s[10:11]
	s_cbranch_execz .LBB0_902
	global_load_dwordx4 v[28:31], v[180:181], off

.LBB0_907:
	ds_read_b128 v[60:63], v201 offset:40960
	ds_read_b128 v[64:67], v201 offset:41984
	ds_read_b128 v[72:75], v201 offset:44032
	ds_read_b128 v[76:79], v201 offset:43008
	ds_read_b128 v[84:87], v201 offset:47104
	ds_read_b128 v[88:91], v201 offset:48128
	ds_read_b128 v[190:193], v201 offset:50176
	ds_read_b128 v[204:207], v201 offset:49152
	s_waitcnt lgkmcnt(7)
	v_mfma_f32_16x16x32_bf16 v[68:71], v[60:63], v[12:15], v[44:47]
	v_exp_f32_e32 v149, v149
	v_exp_f32_e32 v151, v151
	v_mfma_f32_16x16x32_bf16 v[60:63], v[60:63], v[16:19], v[48:51]
	v_exp_f32_e32 v143, v143
	v_exp_f32_e32 v133, v133
	s_waitcnt lgkmcnt(3)
	v_mfma_f32_16x16x32_bf16 v[186:189], v[84:87], v[12:15], v[44:47]
	v_exp_f32_e32 v135, v135
	v_exp_f32_e32 v127, v127
	v_mfma_f32_16x16x32_bf16 v[84:87], v[84:87], v[16:19], v[48:51]
	v_exp_f32_e32 v249, v148
	v_exp_f32_e32 v248, v152
	v_mfma_f32_16x16x32_bf16 v[80:83], v[72:75], v[12:15], v[44:47]
	v_exp_f32_e32 v148, v153
	v_mfma_f32_16x16x32_bf16 v[72:75], v[72:75], v[16:19], v[48:51]
	v_exp_f32_e32 v153, v150
	v_exp_f32_e32 v152, v154
	s_waitcnt lgkmcnt(1)
	v_mfma_f32_16x16x32_bf16 v[208:211], v[190:193], v[12:15], v[44:47]
	v_exp_f32_e32 v150, v155
	v_mfma_f32_16x16x32_bf16 v[190:193], v[190:193], v[16:19], v[48:51]
	v_exp_f32_e32 v155, v141
	v_exp_f32_e32 v154, v145
	v_mfma_f32_16x16x32_bf16 v[68:71], v[64:67], v[4:7], v[68:71]
	v_exp_f32_e32 v145, v142
	v_mfma_f32_16x16x32_bf16 v[60:63], v[64:67], v[20:23], v[60:63]
	v_exp_f32_e32 v142, v147
	ds_read_b128 v[64:67], v201 offset:45056
	ds_read_b128 v[212:215], v201 offset:46080
	v_mfma_f32_16x16x32_bf16 v[216:219], v[88:91], v[20:23], v[84:87]
	v_exp_f32_e32 v141, v132
	v_exp_f32_e32 v132, v137
	v_exp_f32_e32 v251, v140
	ds_read_b128 v[84:87], v201 offset:51200
	ds_read_b128 v[220:223], v201 offset:52224
	s_waitcnt lgkmcnt(3)
	v_mfma_f32_16x16x32_bf16 v[80:83], v[64:67], v[4:7], v[80:83]
	v_exp_f32_e32 v250, v144
	v_mfma_f32_16x16x32_bf16 v[64:67], v[64:67], v[20:23], v[72:75]
	v_exp_f32_e32 v144, v146
	v_exp_f32_e32 v140, v136
	v_mfma_f32_16x16x32_bf16 v[72:75], v[88:91], v[4:7], v[186:189]
	v_exp_f32_e32 v137, v134
	s_waitcnt lgkmcnt(1)
	v_mfma_f32_16x16x32_bf16 v[188:191], v[84:87], v[20:23], v[190:193]
	v_exp_f32_e32 v136, v138
	v_exp_f32_e32 v134, v139
	v_mfma_f32_16x16x32_bf16 v[88:91], v[76:79], v[24:27], v[60:63]
	v_exp_f32_e32 v139, v124
	v_mfma_f32_16x16x32_bf16 v[60:63], v[204:207], v[8:11], v[72:75]
	v_exp_f32_e32 v138, v128
	s_waitcnt lgkmcnt(0)
	v_mfma_f32_16x16x32_bf16 v[72:75], v[220:223], v[24:27], v[188:191]
	v_exp_f32_e32 v147, v125
	ds_read_b128 v[190:193], v203 offset:16384
	v_mfma_f32_16x16x32_bf16 v[208:211], v[84:87], v[4:7], v[208:211]
	v_exp_f32_e32 v146, v129
	v_mfma_f32_16x16x32_bf16 v[84:87], v[76:79], v[8:11], v[68:71]
	v_exp_f32_e32 v125, v126
	v_mfma_f32_16x16x32_bf16 v[76:79], v[212:215], v[8:11], v[80:83]
	v_exp_f32_e32 v124, v130
	v_mfma_f32_16x16x32_bf16 v[80:83], v[212:215], v[24:27], v[64:67]
	v_exp_f32_e32 v126, v131
	v_mfma_f32_16x16x32_bf16 v[68:71], v[204:207], v[24:27], v[216:219]
	ds_read_b128 v[212:215], v203 offset:18432
	s_nop 1
	ds_read_b128 v[216:219], v203 offset:17408
	v_cvt_pk_bf16_f32 v204, v249, v149
	v_cvt_pk_bf16_f32 v205, v153, v151
	v_mfma_f32_16x16x32_bf16 v[64:67], v[220:223], v[8:11], v[208:211]
	v_cvt_pk_bf16_f32 v206, v251, v155
	v_cvt_pk_bf16_f32 v207, v145, v143
	v_cvt_pk_bf16_f32 v208, v248, v148
	v_cvt_pk_bf16_f32 v209, v152, v150
	v_cvt_pk_bf16_f32 v210, v250, v154
	v_cvt_pk_bf16_f32 v211, v144, v142
	s_waitcnt lgkmcnt(2)
	v_mfma_f32_16x16x32_bf16 v[120:123], v[190:193], v[204:207], v[120:123]
	v_mfma_f32_16x16x32_bf16 v[116:119], v[190:193], v[208:211], v[116:119]
	ds_read_b128 v[190:193], v203 offset:20480
	ds_read_b128 v[220:223], v203 offset:19456
	s_waitcnt lgkmcnt(3)
	v_mfma_f32_16x16x32_bf16 v[112:115], v[212:215], v[204:207], v[112:115]
	v_mfma_f32_16x16x32_bf16 v[108:111], v[212:215], v[208:211], v[108:111]
	ds_read_b128 v[212:215], v203 offset:22528
	ds_read_b128 v[224:227], v203 offset:21504
	ds_read_b128 v[232:235], v203 offset:23552
	s_waitcnt lgkmcnt(4)
	v_mfma_f32_16x16x32_bf16 v[228:231], v[190:193], v[204:207], v[104:107]
	v_mfma_f32_16x16x32_bf16 v[190:193], v[190:193], v[208:211], v[100:103]
	s_waitcnt lgkmcnt(2)
	v_mfma_f32_16x16x32_bf16 v[92:95], v[212:215], v[204:207], v[92:95]
	v_cvt_pk_bf16_f32 v204, v141, v133
	v_cvt_pk_bf16_f32 v205, v137, v135
	v_cvt_pk_bf16_f32 v206, v139, v147
	v_mfma_f32_16x16x32_bf16 v[128:131], v[212:215], v[208:211], v[96:99]
	v_cvt_pk_bf16_f32 v207, v125, v127
	v_cvt_pk_bf16_f32 v208, v140, v132
	v_cvt_pk_bf16_f32 v209, v136, v134
	v_cvt_pk_bf16_f32 v210, v138, v146
	v_cvt_pk_bf16_f32 v211, v124, v126
	v_mfma_f32_16x16x32_bf16 v[120:123], v[216:219], v[204:207], v[120:123]
	s_nop 0
	v_mfma_f32_16x16x32_bf16 v[104:107], v[216:219], v[208:211], v[116:119]
	v_max3_f32 v246, v88, v89, v90
	v_max3_f32 v247, v84, v85, v86
	v_mfma_f32_16x16x32_bf16 v[116:119], v[220:223], v[204:207], v[112:115]
	v_max3_f32 v246, v246, v91, v80
	v_max3_f32 v247, v247, v87, v76
	v_mfma_f32_16x16x32_bf16 v[100:103], v[220:223], v[208:211], v[108:111]
	v_max3_f32 v246, v246, v81, v82
	v_max3_f32 v247, v247, v77, v78
	s_waitcnt lgkmcnt(1)
	v_mfma_f32_16x16x32_bf16 v[112:115], v[224:227], v[204:207], v[228:231]
	v_max3_f32 v246, v246, v83, v68
	v_max3_f32 v247, v247, v79, v60
	v_mfma_f32_16x16x32_bf16 v[96:99], v[224:227], v[208:211], v[190:193]
	v_max3_f32 v246, v246, v69, v70
	v_max3_f32 v247, v247, v61, v62
	s_waitcnt lgkmcnt(0)
	v_mfma_f32_16x16x32_bf16 v[108:111], v[232:235], v[204:207], v[92:95]
	v_max3_f32 v246, v246, v71, v72
	v_max3_f32 v247, v247, v63, v64
	v_mfma_f32_16x16x32_bf16 v[92:95], v[232:235], v[208:211], v[128:131]
	v_max3_f32 v246, v246, v73, v74
	v_max3_f32 v247, v247, v65, v66
	s_waitcnt vmcnt(0)
	ds_write_b128 v197, v[52:55]
	s_and_saveexec_b64 s[16:17], s[10:11]
	ds_write_b128 v199, v[28:31]
	s_or_b64 exec, exec, s[16:17]
; DI void attn_phase(LAS unsigned char* lds, const int wid, const bf16_t* Q, const bf16_t* Kn, const bf16_t* Kr, const bf16_t* Vt, bf16_t* O, int G, int c) {
;     ...
;         for (int kt = 0; kt < NKT; kt += 2) {
;             ATT_STEP(kt, bkn, bkr, bvt, akn, akr, avt, sa, sb);
;             ATT_STEP(kt + 1, akn, akr, avt, bkn, bkr, bvt, sb, sa);
;         }
.LBB0_911:
	ds_write2_b64 v1, v[56:57], v[58:59] offset1:32
	v_pk_add_f32 v[236:237], v[248:249], v[250:251]
	v_pk_add_f32 v[238:239], v[148:149], v[154:155]
	v_pk_add_f32 v[240:241], v[144:145], v[152:153]
	v_pk_add_f32 v[242:243], v[142:143], v[150:151]
	v_pk_add_f32 v[236:237], v[236:237], v[140:141]
	v_pk_add_f32 v[238:239], v[238:239], v[132:133]
	v_pk_add_f32 v[240:241], v[136:137], v[240:241]
	v_pk_add_f32 v[242:243], v[134:135], v[242:243]
	v_pk_add_f32 v[236:237], v[236:237], v[138:139]
	v_pk_add_f32 v[238:239], v[238:239], v[146:147]
	v_pk_add_f32 v[240:241], v[124:125], v[240:241]
	v_pk_add_f32 v[242:243], v[126:127], v[242:243]
	s_add_i32 s26, s26, 2
	v_pk_add_f32 v[240:241], v[240:241], v[242:243]
	v_pk_add_f32 v[236:237], v[236:237], v[238:239]
	v_lshl_add_u64 v[2:3], v[2:3], 0, s[42:43]
	v_pk_add_f32 v[236:237], v[236:237], v[240:241]
	v_lshl_add_u64 v[180:181], v[180:181], 0, s[44:45]
	v_pk_add_f32 v[184:185], v[184:185], v[236:237]
	v_lshl_add_u64 v[182:183], v[182:183], 0, s[46:47]
	s_cmpk_gt_u32 s26, 0x7f
	s_waitcnt lgkmcnt(0)
	s_barrier
	s_cbranch_scc1 .Lattn_exit
	v_lshl_add_u64 v[186:187], v[182:183], 0, v[166:167]
	v_lshl_add_u64 v[32:33], v[186:187], 0, s[52:53]
	global_load_dwordx4 v[32:35], v[32:33], off
	s_and_saveexec_b64 s[14:15], s[10:11]
	s_cbranch_execz .Lattn2_890
	global_load_dwordx4 v[36:39], v[180:181], off offset:-4096

.Lattn2_895:
	ds_read_b128 v[124:127], v201 offset:53248
	ds_read_b128 v[128:131], v201 offset:54272
	ds_read_b128 v[136:139], v201 offset:56320
	ds_read_b128 v[140:143], v201 offset:55296
	ds_read_b128 v[148:151], v201 offset:59392
	ds_read_b128 v[152:155], v201 offset:60416
	ds_read_b128 v[204:207], v201 offset:62464
	ds_read_b128 v[208:211], v201 offset:61440
	s_waitcnt lgkmcnt(7)
	v_mfma_f32_16x16x32_bf16 v[132:135], v[124:127], v[12:15], v[44:47]
	v_exp_f32_e32 v195, v84
	v_exp_f32_e32 v194, v88
	v_mfma_f32_16x16x32_bf16 v[124:127], v[124:127], v[16:19], v[48:51]
	v_exp_f32_e32 v88, v91
	v_exp_f32_e32 v84, v81
	s_waitcnt lgkmcnt(3)
	v_mfma_f32_16x16x32_bf16 v[190:193], v[148:151], v[12:15], v[44:47]
	v_exp_f32_e32 v81, v78
	v_exp_f32_e32 v79, v79
	v_mfma_f32_16x16x32_bf16 v[148:151], v[148:151], v[16:19], v[48:51]
	v_exp_f32_e32 v78, v83
	v_exp_f32_e32 v61, v61
	v_mfma_f32_16x16x32_bf16 v[144:147], v[136:139], v[12:15], v[44:47]
	v_exp_f32_e32 v63, v63
	v_exp_f32_e32 v83, v64
	v_mfma_f32_16x16x32_bf16 v[136:139], v[136:139], v[16:19], v[48:51]
	v_exp_f32_e32 v64, v74
	v_exp_f32_e32 v67, v67
	s_waitcnt lgkmcnt(1)
	v_mfma_f32_16x16x32_bf16 v[212:215], v[204:207], v[12:15], v[44:47]
	v_exp_f32_e32 v250, v90
	v_mfma_f32_16x16x32_bf16 v[204:207], v[204:207], v[16:19], v[48:51]
	v_mfma_f32_16x16x32_bf16 v[132:135], v[128:131], v[4:7], v[132:135]
	v_mfma_f32_16x16x32_bf16 v[124:127], v[128:131], v[20:23], v[124:127]
	ds_read_b128 v[128:131], v201 offset:57344
	ds_read_b128 v[216:219], v201 offset:58368
	v_mfma_f32_16x16x32_bf16 v[220:223], v[152:155], v[20:23], v[148:151]
	v_exp_f32_e32 v249, v85
	v_exp_f32_e32 v248, v89
	v_exp_f32_e32 v251, v86
	ds_read_b128 v[148:151], v201 offset:63488
	ds_read_b128 v[224:227], v201 offset:64512
	s_waitcnt lgkmcnt(3)
	v_mfma_f32_16x16x32_bf16 v[144:147], v[128:131], v[4:7], v[144:147]
	v_exp_f32_e32 v89, v87
	v_exp_f32_e32 v87, v76
	v_mfma_f32_16x16x32_bf16 v[128:131], v[128:131], v[20:23], v[136:139]
	v_exp_f32_e32 v86, v80
	s_waitcnt lgkmcnt(1)
	v_mfma_f32_16x16x32_bf16 v[204:207], v[148:151], v[20:23], v[204:207]
	v_exp_f32_e32 v85, v77
	v_exp_f32_e32 v80, v82
	v_mfma_f32_16x16x32_bf16 v[136:139], v[152:155], v[4:7], v[190:193]
	v_exp_f32_e32 v77, v60
	v_mfma_f32_16x16x32_bf16 v[212:215], v[148:151], v[4:7], v[212:215]
	v_exp_f32_e32 v76, v68
	v_exp_f32_e32 v60, v69
	v_mfma_f32_16x16x32_bf16 v[148:151], v[140:143], v[8:11], v[132:135]
	v_exp_f32_e32 v69, v62
	v_mfma_f32_16x16x32_bf16 v[152:155], v[140:143], v[24:27], v[124:127]
	v_exp_f32_e32 v68, v70
	v_exp_f32_e32 v62, v71
	v_mfma_f32_16x16x32_bf16 v[140:143], v[216:219], v[8:11], v[144:147]
	v_exp_f32_e32 v82, v72
	v_mfma_f32_16x16x32_bf16 v[144:147], v[216:219], v[24:27], v[128:131]
	v_exp_f32_e32 v71, v65
	v_exp_f32_e32 v70, v73
	s_waitcnt lgkmcnt(0)
	v_mfma_f32_16x16x32_bf16 v[128:131], v[224:227], v[24:27], v[204:207]
	v_exp_f32_e32 v65, v66
	ds_read_b128 v[204:207], v203 offset:24576
	v_mfma_f32_16x16x32_bf16 v[132:135], v[208:211], v[8:11], v[136:139]
	v_exp_f32_e32 v66, v75
	v_cvt_pk_bf16_f32 v90, v77, v61
	v_mfma_f32_16x16x32_bf16 v[136:139], v[208:211], v[24:27], v[220:223]
	v_cvt_pk_bf16_f32 v208, v195, v249
	v_cvt_pk_bf16_f32 v209, v251, v89
	v_cvt_pk_bf16_f32 v210, v87, v85
	v_mfma_f32_16x16x32_bf16 v[124:127], v[224:227], v[8:11], v[212:215]
	v_cvt_pk_bf16_f32 v211, v81, v79
	ds_read_b128 v[216:219], v203 offset:26624
	ds_read_b128 v[220:223], v203 offset:25600
	v_cvt_pk_bf16_f32 v212, v194, v248
	v_cvt_pk_bf16_f32 v213, v250, v88
	v_cvt_pk_bf16_f32 v214, v86, v84
	v_cvt_pk_bf16_f32 v215, v80, v78
	s_waitcnt lgkmcnt(2)
	v_mfma_f32_16x16x32_bf16 v[120:123], v[204:207], v[208:211], v[120:123]
	v_cvt_pk_bf16_f32 v91, v69, v63
	v_mfma_f32_16x16x32_bf16 v[104:107], v[204:207], v[212:215], v[104:107]
	ds_read_b128 v[204:207], v203 offset:28672
	ds_read_b128 v[224:227], v203 offset:27648
	s_waitcnt lgkmcnt(3)
	v_mfma_f32_16x16x32_bf16 v[228:231], v[216:219], v[208:211], v[116:119]
	v_mfma_f32_16x16x32_bf16 v[100:103], v[216:219], v[212:215], v[100:103]
	s_nop 1
	ds_read_b128 v[116:119], v203 offset:30720
	ds_read_b128 v[216:219], v203 offset:29696
	s_waitcnt lgkmcnt(3)
	v_mfma_f32_16x16x32_bf16 v[232:235], v[204:207], v[208:211], v[112:115]
	v_mfma_f32_16x16x32_bf16 v[96:99], v[204:207], v[212:215], v[96:99]
	ds_read_b128 v[204:207], v203 offset:31744
	s_waitcnt lgkmcnt(2)
	v_mfma_f32_16x16x32_bf16 v[208:211], v[116:119], v[208:211], v[108:111]
	v_mfma_f32_16x16x32_bf16 v[72:75], v[116:119], v[212:215], v[92:95]
	v_cvt_pk_bf16_f32 v212, v76, v60
	v_cvt_pk_bf16_f32 v213, v68, v62
	v_cvt_pk_bf16_f32 v214, v82, v70
	v_cvt_pk_bf16_f32 v92, v83, v71
	v_cvt_pk_bf16_f32 v93, v65, v67
	v_cvt_pk_bf16_f32 v215, v64, v66
	s_nop 0
	v_mfma_f32_16x16x32_bf16 v[120:123], v[220:223], v[90:93], v[120:123]
	v_mfma_f32_16x16x32_bf16 v[116:119], v[220:223], v[212:215], v[104:107]
	v_max3_f32 v244, v152, v153, v154
	v_max3_f32 v245, v148, v149, v150
	v_mfma_f32_16x16x32_bf16 v[112:115], v[224:227], v[90:93], v[228:231]
	v_max3_f32 v244, v244, v155, v144
	v_max3_f32 v245, v245, v151, v140
	v_mfma_f32_16x16x32_bf16 v[108:111], v[224:227], v[212:215], v[100:103]
	v_max3_f32 v244, v244, v145, v146
	v_max3_f32 v245, v245, v141, v142
	s_waitcnt lgkmcnt(1)
	v_mfma_f32_16x16x32_bf16 v[104:107], v[216:219], v[90:93], v[232:235]
	v_max3_f32 v244, v244, v147, v136
	v_max3_f32 v245, v245, v143, v132
	v_mfma_f32_16x16x32_bf16 v[100:103], v[216:219], v[212:215], v[96:99]
	v_max3_f32 v244, v244, v137, v138
	v_max3_f32 v245, v245, v133, v134
	s_waitcnt lgkmcnt(0)
	v_mfma_f32_16x16x32_bf16 v[92:95], v[204:207], v[90:93], v[208:211]
	v_max3_f32 v244, v244, v139, v128
	v_max3_f32 v245, v245, v135, v124
	v_mfma_f32_16x16x32_bf16 v[96:99], v[204:207], v[212:215], v[72:75]
	v_max3_f32 v244, v244, v129, v130
	v_max3_f32 v245, v245, v125, v126
	s_waitcnt vmcnt(0)
	ds_write_b128 v197, v[32:35] offset:12288
	s_and_saveexec_b64 s[16:17], s[10:11]
	ds_write_b128 v199, v[36:39] offset:12288
	s_or_b64 exec, exec, s[16:17]
.Lattn2_899:
	ds_write2_b64 v177, v[40:41], v[42:43] offset1:32
	v_lshl_add_u64 v[52:53], v[186:187], 0, s[58:59]
	global_load_dwordx4 v[52:55], v[52:53], off
	s_and_saveexec_b64 s[16:17], s[10:11]
	s_cbranch_execz .Lattn2_902
	global_load_dwordx4 v[28:31], v[180:181], off

.Lattn2_907:
	ds_read_b128 v[60:63], v201
	ds_read_b128 v[64:67], v201 offset:1024
	ds_read_b128 v[72:75], v201 offset:3072
	ds_read_b128 v[76:79], v201 offset:2048
	ds_read_b128 v[84:87], v201 offset:6144
	ds_read_b128 v[88:91], v201 offset:7168
	ds_read_b128 v[190:193], v201 offset:9216
	ds_read_b128 v[204:207], v201 offset:8192
	s_waitcnt lgkmcnt(7)
	v_mfma_f32_16x16x32_bf16 v[68:71], v[60:63], v[12:15], v[44:47]
	v_exp_f32_e32 v149, v149
	v_exp_f32_e32 v151, v151
	v_mfma_f32_16x16x32_bf16 v[60:63], v[60:63], v[16:19], v[48:51]
	v_exp_f32_e32 v143, v143
	v_exp_f32_e32 v133, v133
	s_waitcnt lgkmcnt(3)
	v_mfma_f32_16x16x32_bf16 v[186:189], v[84:87], v[12:15], v[44:47]
	v_exp_f32_e32 v135, v135
	v_exp_f32_e32 v127, v127
	v_mfma_f32_16x16x32_bf16 v[84:87], v[84:87], v[16:19], v[48:51]
	v_exp_f32_e32 v249, v148
	v_exp_f32_e32 v248, v152
	v_mfma_f32_16x16x32_bf16 v[80:83], v[72:75], v[12:15], v[44:47]
	v_exp_f32_e32 v148, v153
	v_mfma_f32_16x16x32_bf16 v[72:75], v[72:75], v[16:19], v[48:51]
	v_exp_f32_e32 v153, v150
	v_exp_f32_e32 v152, v154
	s_waitcnt lgkmcnt(1)
	v_mfma_f32_16x16x32_bf16 v[208:211], v[190:193], v[12:15], v[44:47]
	v_exp_f32_e32 v150, v155
	v_mfma_f32_16x16x32_bf16 v[190:193], v[190:193], v[16:19], v[48:51]
	v_exp_f32_e32 v155, v141
	v_exp_f32_e32 v154, v145
	v_mfma_f32_16x16x32_bf16 v[68:71], v[64:67], v[4:7], v[68:71]
	v_exp_f32_e32 v145, v142
	v_mfma_f32_16x16x32_bf16 v[60:63], v[64:67], v[20:23], v[60:63]
	v_exp_f32_e32 v142, v147
	ds_read_b128 v[64:67], v201 offset:4096
	ds_read_b128 v[212:215], v201 offset:5120
	v_mfma_f32_16x16x32_bf16 v[216:219], v[88:91], v[20:23], v[84:87]
	v_exp_f32_e32 v141, v132
	v_exp_f32_e32 v132, v137
	v_exp_f32_e32 v251, v140
	ds_read_b128 v[84:87], v201 offset:10240
	ds_read_b128 v[220:223], v201 offset:11264
	s_waitcnt lgkmcnt(3)
	v_mfma_f32_16x16x32_bf16 v[80:83], v[64:67], v[4:7], v[80:83]
	v_exp_f32_e32 v250, v144
	v_mfma_f32_16x16x32_bf16 v[64:67], v[64:67], v[20:23], v[72:75]
	v_exp_f32_e32 v144, v146
	v_exp_f32_e32 v140, v136
	v_mfma_f32_16x16x32_bf16 v[72:75], v[88:91], v[4:7], v[186:189]
	v_exp_f32_e32 v137, v134
	s_waitcnt lgkmcnt(1)
	v_mfma_f32_16x16x32_bf16 v[188:191], v[84:87], v[20:23], v[190:193]
	v_exp_f32_e32 v136, v138
	v_exp_f32_e32 v134, v139
	v_mfma_f32_16x16x32_bf16 v[88:91], v[76:79], v[24:27], v[60:63]
	v_exp_f32_e32 v139, v124
	v_mfma_f32_16x16x32_bf16 v[60:63], v[204:207], v[8:11], v[72:75]
	v_exp_f32_e32 v138, v128
	s_waitcnt lgkmcnt(0)
	v_mfma_f32_16x16x32_bf16 v[72:75], v[220:223], v[24:27], v[188:191]
	v_exp_f32_e32 v147, v125
	ds_read_b128 v[190:193], v200 offset:32768
	v_mfma_f32_16x16x32_bf16 v[208:211], v[84:87], v[4:7], v[208:211]
	v_exp_f32_e32 v146, v129
	v_mfma_f32_16x16x32_bf16 v[84:87], v[76:79], v[8:11], v[68:71]
	v_exp_f32_e32 v125, v126
	v_mfma_f32_16x16x32_bf16 v[76:79], v[212:215], v[8:11], v[80:83]
	v_exp_f32_e32 v124, v130
	v_mfma_f32_16x16x32_bf16 v[80:83], v[212:215], v[24:27], v[64:67]
	v_exp_f32_e32 v126, v131
	v_mfma_f32_16x16x32_bf16 v[68:71], v[204:207], v[24:27], v[216:219]
	ds_read_b128 v[212:215], v200 offset:34816
	s_nop 1
	ds_read_b128 v[216:219], v200 offset:33792
	v_cvt_pk_bf16_f32 v204, v249, v149
	v_cvt_pk_bf16_f32 v205, v153, v151
	v_mfma_f32_16x16x32_bf16 v[64:67], v[220:223], v[8:11], v[208:211]
	v_cvt_pk_bf16_f32 v206, v251, v155
	v_cvt_pk_bf16_f32 v207, v145, v143
	v_cvt_pk_bf16_f32 v208, v248, v148
	v_cvt_pk_bf16_f32 v209, v152, v150
	v_cvt_pk_bf16_f32 v210, v250, v154
	v_cvt_pk_bf16_f32 v211, v144, v142
	s_waitcnt lgkmcnt(2)
	v_mfma_f32_16x16x32_bf16 v[120:123], v[190:193], v[204:207], v[120:123]
	v_mfma_f32_16x16x32_bf16 v[116:119], v[190:193], v[208:211], v[116:119]
	ds_read_b128 v[190:193], v200 offset:36864
	ds_read_b128 v[220:223], v200 offset:35840
	s_waitcnt lgkmcnt(3)
	v_mfma_f32_16x16x32_bf16 v[112:115], v[212:215], v[204:207], v[112:115]
	v_mfma_f32_16x16x32_bf16 v[108:111], v[212:215], v[208:211], v[108:111]
	ds_read_b128 v[212:215], v200 offset:38912
	ds_read_b128 v[224:227], v200 offset:37888
	ds_read_b128 v[232:235], v200 offset:39936
	s_waitcnt lgkmcnt(4)
	v_mfma_f32_16x16x32_bf16 v[228:231], v[190:193], v[204:207], v[104:107]
	v_mfma_f32_16x16x32_bf16 v[190:193], v[190:193], v[208:211], v[100:103]
	s_waitcnt lgkmcnt(2)
	v_mfma_f32_16x16x32_bf16 v[92:95], v[212:215], v[204:207], v[92:95]
	v_cvt_pk_bf16_f32 v204, v141, v133
	v_cvt_pk_bf16_f32 v205, v137, v135
	v_cvt_pk_bf16_f32 v206, v139, v147
	v_mfma_f32_16x16x32_bf16 v[128:131], v[212:215], v[208:211], v[96:99]
	v_cvt_pk_bf16_f32 v207, v125, v127
	v_cvt_pk_bf16_f32 v208, v140, v132
	v_cvt_pk_bf16_f32 v209, v136, v134
	v_cvt_pk_bf16_f32 v210, v138, v146
	v_cvt_pk_bf16_f32 v211, v124, v126
	v_mfma_f32_16x16x32_bf16 v[120:123], v[216:219], v[204:207], v[120:123]
	s_nop 0
	v_mfma_f32_16x16x32_bf16 v[104:107], v[216:219], v[208:211], v[116:119]
	v_max3_f32 v246, v88, v89, v90
	v_max3_f32 v247, v84, v85, v86
	v_mfma_f32_16x16x32_bf16 v[116:119], v[220:223], v[204:207], v[112:115]
	v_max3_f32 v246, v246, v91, v80
	v_max3_f32 v247, v247, v87, v76
	v_mfma_f32_16x16x32_bf16 v[100:103], v[220:223], v[208:211], v[108:111]
	v_max3_f32 v246, v246, v81, v82
	v_max3_f32 v247, v247, v77, v78
	s_waitcnt lgkmcnt(1)
	v_mfma_f32_16x16x32_bf16 v[112:115], v[224:227], v[204:207], v[228:231]
	v_max3_f32 v246, v246, v83, v68
	v_max3_f32 v247, v247, v79, v60
	v_mfma_f32_16x16x32_bf16 v[96:99], v[224:227], v[208:211], v[190:193]
	v_max3_f32 v246, v246, v69, v70
	v_max3_f32 v247, v247, v61, v62
	s_waitcnt lgkmcnt(0)
	v_mfma_f32_16x16x32_bf16 v[108:111], v[232:235], v[204:207], v[92:95]
	v_max3_f32 v246, v246, v71, v72
	v_max3_f32 v247, v247, v63, v64
	v_mfma_f32_16x16x32_bf16 v[92:95], v[232:235], v[208:211], v[128:131]
	v_max3_f32 v246, v246, v73, v74
	v_max3_f32 v247, v247, v65, v66
	s_waitcnt vmcnt(0)
	ds_write_b128 v197, v[52:55] offset:40960
	s_and_saveexec_b64 s[16:17], s[10:11]
	ds_write_b128 v199, v[28:31] offset:40960
	s_or_b64 exec, exec, s[16:17]
; DI void attn_phase(LAS unsigned char* lds, const int wid, const bf16_t* Q, const bf16_t* Kn, const bf16_t* Kr, const bf16_t* Vt, bf16_t* O, int G, int c) {
;     ...
;         for (int kt = 0; kt < NKT; kt += 2) {
;             ATT_STEP(kt, bkn, bkr, bvt, akn, akr, avt, sa, sb);
;             ATT_STEP(kt + 1, akn, akr, avt, bkn, bkr, bvt, sb, sa);
;         }
.Lattn2_911:
	ds_write2_b64 v252, v[56:57], v[58:59] offset1:32
	v_pk_add_f32 v[236:237], v[248:249], v[250:251]
	v_pk_add_f32 v[238:239], v[148:149], v[154:155]
	v_pk_add_f32 v[240:241], v[144:145], v[152:153]
	v_pk_add_f32 v[242:243], v[142:143], v[150:151]
	v_pk_add_f32 v[236:237], v[236:237], v[140:141]
	v_pk_add_f32 v[238:239], v[238:239], v[132:133]
	v_pk_add_f32 v[240:241], v[136:137], v[240:241]
	v_pk_add_f32 v[242:243], v[134:135], v[242:243]
	v_pk_add_f32 v[236:237], v[236:237], v[138:139]
	v_pk_add_f32 v[238:239], v[238:239], v[146:147]
	v_pk_add_f32 v[240:241], v[124:125], v[240:241]
	v_pk_add_f32 v[242:243], v[126:127], v[242:243]
	s_add_i32 s26, s26, 2
	v_pk_add_f32 v[240:241], v[240:241], v[242:243]
	v_pk_add_f32 v[236:237], v[236:237], v[238:239]
	v_lshl_add_u64 v[2:3], v[2:3], 0, s[42:43]
	v_pk_add_f32 v[236:237], v[236:237], v[240:241]
	v_lshl_add_u64 v[180:181], v[180:181], 0, s[44:45]
	v_pk_add_f32 v[184:185], v[184:185], v[236:237]
	v_lshl_add_u64 v[182:183], v[182:183], 0, s[46:47]
	s_cmpk_gt_u32 s26, 0x7f
	s_waitcnt lgkmcnt(0)
	s_barrier
	s_cbranch_scc0 .LBB0_887
.Lattn_exit:
	s_waitcnt vmcnt(0)
	s_branch .LBB0_857
